# out-proj epilogue stores (f32 residual stream + bf16 copy) issued write-through (sc1)
# speedup vs baseline: 1.0145x; 1.0001x over previous
; __device__ __forceinline__ unsigned cvt_pk_bf16(float lo, float hi) { unsigned r; asm volatile("v_cvt_pk_bf16_f32 %0, %1, %2" : "=v"(r) : "v"(lo), "v"(hi)); return r; }
; #define EO_LOAD(rr, slot) do { const size_t o_ = (size_t)(row0 + ((rr) >> 2) * 128 + ((rr) & 3) * 16) * DM + col0; _Pragma("unroll") for (int q_ = 0; q_ < 4; ++q_) xr[slot][q_] = *(const f32x4*)(Xin + o_ + (q_ >> 1) * 128 + (q_ & 1) * 16); } while (0)
;     __device__ __forceinline__ void operator()(const f32x4 (&acc)[2][2][4][2], const pg8::Unit& u, int wr, int wc, int fr, int fq) const {
;         asm volatile("" : "+v"(fr), "+v"(fq));
;         const int row0 = u.pm * 256 + wr * 64 + fr, col0 = u.pn * 256 + wc * 32 + 4 * fq;
;         f32x4 xr[3][4];
;     ...
;         EO_LOAD(0, 0); EO_LOAD(1, 1);
; #pragma unroll
;         for (int rr = 0; rr < 8; ++rr) { const int ai = rr >> 2, m = rr & 3, row = row0 + ai * 128 + m * 16; const size_t o = (size_t)row * DM + col0; float s = 0.f;
;             if (rr + 2 < 8) EO_LOAD(rr + 2, (rr + 2) % 3);
; #pragma unroll
;             for (int q = 0; q < 4; ++q) { const int bj = q >> 1, n = q & 1; const size_t idx = o + bj * 128 + n * 16; const f32x4 v = xr[rr % 3][q] + acc[ai][bj][m][n]; *(f32x4*)(Out + idx) = v;
;                 if (ssq) { u32x2 w; w.x = cvt_pk_bf16(v[0], v[1]); w.y = cvt_pk_bf16(v[2], v[3]); *(u32x2*)(HBo + idx) = w; s += (v[0] * v[0] + v[1] * v[1]) + (v[2] * v[2] + v[3] * v[3]); } }
;             if (ssq) { s += __shfl_xor(s, 16); s += __shfl_xor(s, 32); if (fq == 0) atomicAdd(ssq + row, s); } }
.LBB0_124:
	s_lshl_b32 s6, s39, 8
	v_mov_b32_e32 v130, v179
	v_mov_b32_e32 v215, v181
	v_and_b32_e32 v220, 1, v215
	v_mul_u32_u24_e32 v220, 24, v220
	s_add_i32 s6, s6, s44
	v_readlane_b32 s72, v251, 6
	v_add_u32_e32 v190, s6, v130
	s_lshl_b32 s6, s38, 8
	s_or_b32 s6, s6, s45
	v_lshl_add_u32 v192, v215, 2, s6
	v_ashrrev_i32_e32 v191, 31, v190
	v_ashrrev_i32_e32 v193, 31, v192
	v_lshlrev_b64 v[130:131], 13, v[190:191]
	v_lshl_add_u64 v[130:131], s[10:11], 0, v[130:131]
	v_lshlrev_b64 v[132:133], 2, v[192:193]
	v_add_u32_e32 v196, 16, v190
	v_lshl_add_u64 v[130:131], v[130:131], 0, v[132:133]
	v_ashrrev_i32_e32 v197, 31, v196
	global_load_dwordx4 v[198:201], v[130:131], off
	global_load_dwordx4 v[170:173], v[130:131], off offset:64
	global_load_dwordx4 v[166:169], v[130:131], off offset:512
	global_load_dwordx4 v[162:165], v[130:131], off offset:576
	v_lshlrev_b64 v[130:131], 13, v[196:197]
	v_lshl_add_u64 v[130:131], s[10:11], 0, v[130:131]
	v_lshl_add_u64 v[130:131], v[130:131], 0, v[132:133]
	v_add_u32_e32 v194, 32, v190
	global_load_dwordx4 v[158:161], v[130:131], off
	global_load_dwordx4 v[154:157], v[130:131], off offset:64
	global_load_dwordx4 v[150:153], v[130:131], off offset:512
	global_load_dwordx4 v[146:149], v[130:131], off offset:576
	v_lshlrev_b64 v[130:131], 11, v[190:191]
	v_ashrrev_i32_e32 v195, 31, v194
	v_lshl_add_u64 v[218:219], v[130:131], 0, v[192:193]
	v_lshlrev_b64 v[130:131], 13, v[194:195]
	v_lshl_add_u64 v[130:131], s[10:11], 0, v[130:131]
	v_lshl_add_u64 v[130:131], v[130:131], 0, v[132:133]
	global_load_dwordx4 v[142:145], v[130:131], off
	global_load_dwordx4 v[138:141], v[130:131], off offset:64
	global_load_dwordx4 v[134:137], v[130:131], off offset:512
	s_nop 0
	global_load_dwordx4 v[130:133], v[130:131], off offset:576
	v_readlane_b32 s86, v251, 20
	v_readlane_b32 s87, v251, 21
	v_mov_b32_e32 v216, 0
	s_andn2_b64 vcc, exec, s[12:13]
	v_readlane_b32 s73, v251, 7
	v_readlane_b32 s74, v251, 8
	v_readlane_b32 s75, v251, 9
	v_readlane_b32 s76, v251, 10
	v_readlane_b32 s77, v251, 11
	v_readlane_b32 s78, v251, 12
	v_readlane_b32 s79, v251, 13
	v_readlane_b32 s80, v251, 14
	v_readlane_b32 s81, v251, 15
	v_readlane_b32 s82, v251, 16
	v_readlane_b32 s83, v251, 17
	v_readlane_b32 s84, v251, 18
	v_readlane_b32 s85, v251, 19
	s_waitcnt vmcnt(8)
	v_pk_add_f32 v[128:129], v[128:129], v[200:201]
	v_cndmask_b32_e64 v200, 0, 1, s[12:13]
	v_pk_add_f32 v[126:127], v[126:127], v[198:199]
	v_lshl_add_u64 v[198:199], v[218:219], 2, s[86:87]
	v_cmp_ne_u32_e64 s[6:7], 1, v200
	v_lshl_add_u64 v[200:201], v[218:219], 1, s[22:23]
	global_store_dwordx4 v[198:199], v[126:129], off sc1
	s_cbranch_vccnz .LBB0_126
.LBB0_126:
	v_pk_add_f32 v[124:125], v[124:125], v[172:173]
	v_pk_add_f32 v[122:123], v[122:123], v[170:171]
	s_and_b64 vcc, exec, s[6:7]
	global_store_dwordx4 v[198:199], v[122:125], off offset:64 sc1
	s_cbranch_vccnz .LBB0_128
.LBB0_128:
	v_readlane_b32 s54, v250, 12
	v_pk_add_f32 v[120:121], v[120:121], v[168:169]
	v_pk_add_f32 v[118:119], v[118:119], v[166:167]
	s_and_b64 vcc, exec, s[6:7]
	v_readlane_b32 s55, v250, 13
	global_store_dwordx4 v[198:199], v[118:121], off offset:512 sc1
	s_cbranch_vccnz .LBB0_130
.LBB0_130:
	v_pk_add_f32 v[116:117], v[116:117], v[164:165]
	v_pk_add_f32 v[114:115], v[114:115], v[162:163]
	s_and_b64 vcc, exec, s[6:7]
	s_mov_b64 s[36:37], 0
	global_store_dwordx4 v[198:199], v[114:117], off offset:576 sc1
	s_cbranch_vccnz .LBB0_132
	s_mov_b64 s[36:37], s[14:15]
.LBB0_132:
	s_cmp_eq_u64 s[36:37], 0
	v_cmp_eq_u32_e64 s[8:9], 0, v215
	s_cbranch_scc1 .LBB0_136
	v_mul_f32_e32 v216, v126, v126
	v_fmac_f32_e32 v216, v127, v127
	v_fmac_f32_e32 v216, v128, v128
	v_fmac_f32_e32 v216, v129, v129
	v_fmac_f32_e32 v216, v122, v122
	v_fmac_f32_e32 v216, v123, v123
	v_fmac_f32_e32 v216, v124, v124
	v_fmac_f32_e32 v216, v125, v125
	v_fmac_f32_e32 v216, v118, v118
	v_fmac_f32_e32 v216, v119, v119
	v_fmac_f32_e32 v216, v120, v120
	v_fmac_f32_e32 v216, v121, v121
	v_fmac_f32_e32 v216, v114, v114
	v_fmac_f32_e32 v216, v115, v115
	v_fmac_f32_e32 v216, v116, v116
	v_fmac_f32_e32 v216, v117, v117
	v_cvt_pk_bf16_f32 v126, v126, v127
	v_cvt_pk_bf16_f32 v127, v128, v129
	v_cvt_pk_bf16_f32 v128, v122, v123
	v_cvt_pk_bf16_f32 v129, v124, v125
	v_cvt_pk_bf16_f32 v118, v118, v119
	v_cvt_pk_bf16_f32 v119, v120, v121
	v_cvt_pk_bf16_f32 v120, v114, v115
	v_cvt_pk_bf16_f32 v121, v116, v117
	v_add_co_u32_e32 v200, vcc, v220, v200
	s_nop 1
	v_addc_co_u32_e32 v201, vcc, 0, v201, vcc
	v_permlane16_swap_b32_e32 v126, v128
	v_permlane16_swap_b32_e32 v127, v129
	v_permlane16_swap_b32_e32 v118, v120
	v_permlane16_swap_b32_e32 v119, v121
	global_store_dwordx4 v[200:201], v[126:129], off sc1
	global_store_dwordx4 v[200:201], v[118:121], off offset:256 sc1
	v_and_b32_e32 v115, 64, v204
	v_xor_b32_e32 v114, 16, v204
	v_add_u32_e32 v115, 64, v115
	v_cmp_lt_i32_e32 vcc, v114, v115
	v_xor_b32_e32 v116, 32, v204
	s_nop 0
	v_cndmask_b32_e32 v114, v204, v114, vcc
	v_lshlrev_b32_e32 v114, 2, v114
	ds_bpermute_b32 v114, v114, v216
	v_cmp_lt_i32_e32 vcc, v116, v115
	s_waitcnt lgkmcnt(0)
	v_add_f32_e32 v114, v216, v114
	v_cndmask_b32_e32 v115, v204, v116, vcc
	v_lshlrev_b32_e32 v115, 2, v115
	ds_bpermute_b32 v115, v115, v114
	s_and_saveexec_b64 s[38:39], s[8:9]
	s_cbranch_execz .LBB0_135
	v_lshl_add_u64 v[116:117], v[190:191], 2, s[36:37]
	s_waitcnt lgkmcnt(0)
	v_add_f32_e32 v114, v114, v115
	global_atomic_add_f32 v[116:117], v114, off

; __device__ __forceinline__ unsigned cvt_pk_bf16(float lo, float hi) { unsigned r; asm volatile("v_cvt_pk_bf16_f32 %0, %1, %2" : "=v"(r) : "v"(lo), "v"(hi)); return r; }
; #define EO_LOAD(rr, slot) do { const size_t o_ = (size_t)(row0 + ((rr) >> 2) * 128 + ((rr) & 3) * 16) * DM + col0; _Pragma("unroll") for (int q_ = 0; q_ < 4; ++q_) xr[slot][q_] = *(const f32x4*)(Xin + o_ + (q_ >> 1) * 128 + (q_ & 1) * 16); } while (0)
;     __device__ __forceinline__ void operator()(const f32x4 (&acc)[2][2][4][2], const pg8::Unit& u, int wr, int wc, int fr, int fq) const {
;     ...
;         for (int rr = 0; rr < 8; ++rr) { const int ai = rr >> 2, m = rr & 3, row = row0 + ai * 128 + m * 16; const size_t o = (size_t)row * DM + col0; float s = 0.f;
;             if (rr + 2 < 8) EO_LOAD(rr + 2, (rr + 2) % 3);
; #pragma unroll
;             for (int q = 0; q < 4; ++q) { const int bj = q >> 1, n = q & 1; const size_t idx = o + bj * 128 + n * 16; const f32x4 v = xr[rr % 3][q] + acc[ai][bj][m][n]; *(f32x4*)(Out + idx) = v;
;                 if (ssq) { u32x2 w; w.x = cvt_pk_bf16(v[0], v[1]); w.y = cvt_pk_bf16(v[2], v[3]); *(u32x2*)(HBo + idx) = w; s += (v[0] * v[0] + v[1] * v[1]) + (v[2] * v[2] + v[3] * v[3]); } }
;             if (ssq) { s += __shfl_xor(s, 16); s += __shfl_xor(s, 32); if (fq == 0) atomicAdd(ssq + row, s); } }
.Lmy_eo_r1_d:
	v_pk_add_f32 v[112:113], v[112:113], v[160:161]
	v_pk_add_f32 v[110:111], v[110:111], v[158:159]
	v_lshl_add_u64 v[160:161], v[166:167], 2, s[86:87]
	v_mov_b32_e32 v164, 0
	s_and_b64 vcc, exec, s[6:7]
	v_lshl_add_u64 v[158:159], v[166:167], 1, s[22:23]
	v_readlane_b32 s73, v251, 7
	v_readlane_b32 s74, v251, 8
	v_readlane_b32 s75, v251, 9
	v_readlane_b32 s76, v251, 10
	v_readlane_b32 s77, v251, 11
	v_readlane_b32 s78, v251, 12
	v_readlane_b32 s79, v251, 13
	v_readlane_b32 s80, v251, 14
	v_readlane_b32 s81, v251, 15
	v_readlane_b32 s82, v251, 16
	v_readlane_b32 s83, v251, 17
	v_readlane_b32 s84, v251, 18
	v_readlane_b32 s85, v251, 19
	global_store_dwordx4 v[160:161], v[110:113], off sc1
	s_cbranch_vccnz .LBB0_138
.LBB0_138:
	v_pk_add_f32 v[108:109], v[108:109], v[156:157]
	v_pk_add_f32 v[106:107], v[106:107], v[154:155]
	s_and_b64 vcc, exec, s[6:7]
	global_store_dwordx4 v[160:161], v[106:109], off offset:64 sc1
	s_cbranch_vccnz .LBB0_140
.LBB0_140:
	v_pk_add_f32 v[104:105], v[104:105], v[152:153]
	v_pk_add_f32 v[102:103], v[102:103], v[150:151]
	s_and_b64 vcc, exec, s[6:7]
	global_store_dwordx4 v[160:161], v[102:105], off offset:512 sc1
	s_cbranch_vccnz .LBB0_142
.LBB0_142:
	v_pk_add_f32 v[100:101], v[100:101], v[148:149]
	v_pk_add_f32 v[98:99], v[98:99], v[146:147]
	s_and_b64 vcc, exec, s[6:7]
	s_mov_b64 s[36:37], 0
	global_store_dwordx4 v[160:161], v[98:101], off offset:576 sc1
	s_cbranch_vccnz .LBB0_144
	s_mov_b64 s[36:37], s[14:15]
.LBB0_144:
	s_cmp_eq_u64 s[36:37], 0
	s_cbranch_scc1 .LBB0_148
	v_mul_f32_e32 v164, v110, v110
	v_fmac_f32_e32 v164, v111, v111
	v_fmac_f32_e32 v164, v112, v112
	v_fmac_f32_e32 v164, v113, v113
	v_fmac_f32_e32 v164, v106, v106
	v_fmac_f32_e32 v164, v107, v107
	v_fmac_f32_e32 v164, v108, v108
	v_fmac_f32_e32 v164, v109, v109
	v_fmac_f32_e32 v164, v102, v102
	v_fmac_f32_e32 v164, v103, v103
	v_fmac_f32_e32 v164, v104, v104
	v_fmac_f32_e32 v164, v105, v105
	v_fmac_f32_e32 v164, v98, v98
	v_fmac_f32_e32 v164, v99, v99
	v_fmac_f32_e32 v164, v100, v100
	v_fmac_f32_e32 v164, v101, v101
	v_cvt_pk_bf16_f32 v110, v110, v111
	v_cvt_pk_bf16_f32 v111, v112, v113
	v_cvt_pk_bf16_f32 v112, v106, v107
	v_cvt_pk_bf16_f32 v113, v108, v109
	v_cvt_pk_bf16_f32 v102, v102, v103
	v_cvt_pk_bf16_f32 v103, v104, v105
	v_cvt_pk_bf16_f32 v104, v98, v99
	v_cvt_pk_bf16_f32 v105, v100, v101
	v_add_co_u32_e32 v158, vcc, v220, v158
	s_nop 1
	v_addc_co_u32_e32 v159, vcc, 0, v159, vcc
	v_permlane16_swap_b32_e32 v110, v112
	v_permlane16_swap_b32_e32 v111, v113
	v_permlane16_swap_b32_e32 v102, v104
	v_permlane16_swap_b32_e32 v103, v105
	global_store_dwordx4 v[158:159], v[110:113], off sc1
	global_store_dwordx4 v[158:159], v[102:105], off offset:256 sc1
	v_and_b32_e32 v99, 64, v204
	v_xor_b32_e32 v98, 16, v204
	v_add_u32_e32 v99, 64, v99
	v_cmp_lt_i32_e32 vcc, v98, v99
	v_xor_b32_e32 v100, 32, v204
	s_nop 0
	v_cndmask_b32_e32 v98, v204, v98, vcc
	v_lshlrev_b32_e32 v98, 2, v98
	ds_bpermute_b32 v98, v98, v164
	v_cmp_lt_i32_e32 vcc, v100, v99
	s_waitcnt lgkmcnt(0)
	v_add_f32_e32 v98, v164, v98
	v_cndmask_b32_e32 v99, v204, v100, vcc
	v_lshlrev_b32_e32 v99, 2, v99
	ds_bpermute_b32 v99, v99, v98
	s_and_saveexec_b64 s[38:39], s[8:9]
	s_cbranch_execz .LBB0_147
	v_lshl_add_u64 v[100:101], v[190:191], 2, s[36:37]
	s_waitcnt lgkmcnt(0)
	v_add_f32_e32 v98, v98, v99
	global_atomic_add_f32 v[100:101], v98, off offset:64

; __device__ __forceinline__ unsigned cvt_pk_bf16(float lo, float hi) { unsigned r; asm volatile("v_cvt_pk_bf16_f32 %0, %1, %2" : "=v"(r) : "v"(lo), "v"(hi)); return r; }
; #define EO_LOAD(rr, slot) do { const size_t o_ = (size_t)(row0 + ((rr) >> 2) * 128 + ((rr) & 3) * 16) * DM + col0; _Pragma("unroll") for (int q_ = 0; q_ < 4; ++q_) xr[slot][q_] = *(const f32x4*)(Xin + o_ + (q_ >> 1) * 128 + (q_ & 1) * 16); } while (0)
;     __device__ __forceinline__ void operator()(const f32x4 (&acc)[2][2][4][2], const pg8::Unit& u, int wr, int wc, int fr, int fq) const {
;     ...
;         for (int rr = 0; rr < 8; ++rr) { const int ai = rr >> 2, m = rr & 3, row = row0 + ai * 128 + m * 16; const size_t o = (size_t)row * DM + col0; float s = 0.f;
;             if (rr + 2 < 8) EO_LOAD(rr + 2, (rr + 2) % 3);
; #pragma unroll
;             for (int q = 0; q < 4; ++q) { const int bj = q >> 1, n = q & 1; const size_t idx = o + bj * 128 + n * 16; const f32x4 v = xr[rr % 3][q] + acc[ai][bj][m][n]; *(f32x4*)(Out + idx) = v;
;                 if (ssq) { u32x2 w; w.x = cvt_pk_bf16(v[0], v[1]); w.y = cvt_pk_bf16(v[2], v[3]); *(u32x2*)(HBo + idx) = w; s += (v[0] * v[0] + v[1] * v[1]) + (v[2] * v[2] + v[3] * v[3]); } }
;             if (ssq) { s += __shfl_xor(s, 16); s += __shfl_xor(s, 32); if (fq == 0) atomicAdd(ssq + row, s); } }
.Lmy_eo_r2_d:
	v_pk_add_f32 v[96:97], v[96:97], v[144:145]
	v_pk_add_f32 v[94:95], v[94:95], v[142:143]
	v_lshl_add_u64 v[144:145], v[150:151], 2, s[86:87]
	v_mov_b32_e32 v148, 0
	s_and_b64 vcc, exec, s[6:7]
	v_lshl_add_u64 v[142:143], v[150:151], 1, s[22:23]
	v_readlane_b32 s73, v251, 7
	v_readlane_b32 s74, v251, 8
	v_readlane_b32 s75, v251, 9
	v_readlane_b32 s76, v251, 10
	v_readlane_b32 s77, v251, 11
	v_readlane_b32 s78, v251, 12
	v_readlane_b32 s79, v251, 13
	v_readlane_b32 s80, v251, 14
	v_readlane_b32 s81, v251, 15
	v_readlane_b32 s82, v251, 16
	v_readlane_b32 s83, v251, 17
	v_readlane_b32 s84, v251, 18
	v_readlane_b32 s85, v251, 19
	global_store_dwordx4 v[144:145], v[94:97], off sc1
	s_cbranch_vccnz .LBB0_150
.LBB0_150:
	v_pk_add_f32 v[92:93], v[92:93], v[140:141]
	v_pk_add_f32 v[90:91], v[90:91], v[138:139]
	s_and_b64 vcc, exec, s[6:7]
	global_store_dwordx4 v[144:145], v[90:93], off offset:64 sc1
	s_cbranch_vccnz .LBB0_152
.LBB0_152:
	v_pk_add_f32 v[88:89], v[88:89], v[136:137]
	v_pk_add_f32 v[86:87], v[86:87], v[134:135]
	s_and_b64 vcc, exec, s[6:7]
	global_store_dwordx4 v[144:145], v[86:89], off offset:512 sc1
	s_cbranch_vccnz .LBB0_154
.LBB0_154:
	v_pk_add_f32 v[84:85], v[84:85], v[132:133]
	v_pk_add_f32 v[82:83], v[82:83], v[130:131]
	s_and_b64 vcc, exec, s[6:7]
	s_mov_b64 s[36:37], 0
	global_store_dwordx4 v[144:145], v[82:85], off offset:576 sc1
	s_cbranch_vccnz .LBB0_156
	s_mov_b64 s[36:37], s[14:15]
.LBB0_156:
	s_cmp_eq_u64 s[36:37], 0
	s_cbranch_scc1 .LBB0_160
	v_mul_f32_e32 v148, v94, v94
	v_fmac_f32_e32 v148, v95, v95
	v_fmac_f32_e32 v148, v96, v96
	v_fmac_f32_e32 v148, v97, v97
	v_fmac_f32_e32 v148, v90, v90
	v_fmac_f32_e32 v148, v91, v91
	v_fmac_f32_e32 v148, v92, v92
	v_fmac_f32_e32 v148, v93, v93
	v_fmac_f32_e32 v148, v86, v86
	v_fmac_f32_e32 v148, v87, v87
	v_fmac_f32_e32 v148, v88, v88
	v_fmac_f32_e32 v148, v89, v89
	v_fmac_f32_e32 v148, v82, v82
	v_fmac_f32_e32 v148, v83, v83
	v_fmac_f32_e32 v148, v84, v84
	v_fmac_f32_e32 v148, v85, v85
	v_cvt_pk_bf16_f32 v94, v94, v95
	v_cvt_pk_bf16_f32 v95, v96, v97
	v_cvt_pk_bf16_f32 v96, v90, v91
	v_cvt_pk_bf16_f32 v97, v92, v93
	v_cvt_pk_bf16_f32 v86, v86, v87
	v_cvt_pk_bf16_f32 v87, v88, v89
	v_cvt_pk_bf16_f32 v88, v82, v83
	v_cvt_pk_bf16_f32 v89, v84, v85
	v_add_co_u32_e32 v142, vcc, v220, v142
	s_nop 1
	v_addc_co_u32_e32 v143, vcc, 0, v143, vcc
	v_permlane16_swap_b32_e32 v94, v96
	v_permlane16_swap_b32_e32 v95, v97
	v_permlane16_swap_b32_e32 v86, v88
	v_permlane16_swap_b32_e32 v87, v89
	global_store_dwordx4 v[142:143], v[94:97], off sc1
	global_store_dwordx4 v[142:143], v[86:89], off offset:256 sc1
	v_and_b32_e32 v83, 64, v204
	v_xor_b32_e32 v82, 16, v204
	v_add_u32_e32 v83, 64, v83
	v_cmp_lt_i32_e32 vcc, v82, v83
	v_xor_b32_e32 v84, 32, v204
	s_nop 0
	v_cndmask_b32_e32 v82, v204, v82, vcc
	v_lshlrev_b32_e32 v82, 2, v82
	ds_bpermute_b32 v82, v82, v148
	v_cmp_lt_i32_e32 vcc, v84, v83
	s_waitcnt lgkmcnt(0)
	v_add_f32_e32 v82, v148, v82
	v_cndmask_b32_e32 v83, v204, v84, vcc
	v_lshlrev_b32_e32 v83, 2, v83
	ds_bpermute_b32 v83, v83, v82
	s_and_saveexec_b64 s[38:39], s[8:9]
	s_cbranch_execz .LBB0_159
	v_lshl_add_u64 v[84:85], v[190:191], 2, s[36:37]
	s_waitcnt lgkmcnt(0)
	v_add_f32_e32 v82, v82, v83
	global_atomic_add_f32 v[84:85], v82, off offset:128

; __device__ __forceinline__ unsigned cvt_pk_bf16(float lo, float hi) { unsigned r; asm volatile("v_cvt_pk_bf16_f32 %0, %1, %2" : "=v"(r) : "v"(lo), "v"(hi)); return r; }
; #define EO_LOAD(rr, slot) do { const size_t o_ = (size_t)(row0 + ((rr) >> 2) * 128 + ((rr) & 3) * 16) * DM + col0; _Pragma("unroll") for (int q_ = 0; q_ < 4; ++q_) xr[slot][q_] = *(const f32x4*)(Xin + o_ + (q_ >> 1) * 128 + (q_ & 1) * 16); } while (0)
;     __device__ __forceinline__ void operator()(const f32x4 (&acc)[2][2][4][2], const pg8::Unit& u, int wr, int wc, int fr, int fq) const {
;     ...
;         for (int rr = 0; rr < 8; ++rr) { const int ai = rr >> 2, m = rr & 3, row = row0 + ai * 128 + m * 16; const size_t o = (size_t)row * DM + col0; float s = 0.f;
;             if (rr + 2 < 8) EO_LOAD(rr + 2, (rr + 2) % 3);
; #pragma unroll
;             for (int q = 0; q < 4; ++q) { const int bj = q >> 1, n = q & 1; const size_t idx = o + bj * 128 + n * 16; const f32x4 v = xr[rr % 3][q] + acc[ai][bj][m][n]; *(f32x4*)(Out + idx) = v;
;                 if (ssq) { u32x2 w; w.x = cvt_pk_bf16(v[0], v[1]); w.y = cvt_pk_bf16(v[2], v[3]); *(u32x2*)(HBo + idx) = w; s += (v[0] * v[0] + v[1] * v[1]) + (v[2] * v[2] + v[3] * v[3]); } }
;             if (ssq) { s += __shfl_xor(s, 16); s += __shfl_xor(s, 32); if (fq == 0) atomicAdd(ssq + row, s); } }
.Lmy_eo_r3_d:
	v_pk_add_f32 v[80:81], v[80:81], v[128:129]
	v_pk_add_f32 v[78:79], v[78:79], v[126:127]
	v_lshl_add_u64 v[128:129], v[134:135], 2, s[86:87]
	v_mov_b32_e32 v132, 0
	s_and_b64 vcc, exec, s[6:7]
	v_lshl_add_u64 v[126:127], v[134:135], 1, s[22:23]
	v_readlane_b32 s73, v251, 7
	v_readlane_b32 s74, v251, 8
	v_readlane_b32 s75, v251, 9
	v_readlane_b32 s76, v251, 10
	v_readlane_b32 s77, v251, 11
	v_readlane_b32 s78, v251, 12
	v_readlane_b32 s79, v251, 13
	v_readlane_b32 s80, v251, 14
	v_readlane_b32 s81, v251, 15
	v_readlane_b32 s82, v251, 16
	v_readlane_b32 s83, v251, 17
	v_readlane_b32 s84, v251, 18
	v_readlane_b32 s85, v251, 19
	global_store_dwordx4 v[128:129], v[78:81], off sc1
	s_cbranch_vccnz .LBB0_162
.LBB0_162:
	v_pk_add_f32 v[76:77], v[76:77], v[124:125]
	v_pk_add_f32 v[74:75], v[74:75], v[122:123]
	s_and_b64 vcc, exec, s[6:7]
	global_store_dwordx4 v[128:129], v[74:77], off offset:64 sc1
	s_cbranch_vccnz .LBB0_164
.LBB0_164:
	v_pk_add_f32 v[72:73], v[72:73], v[120:121]
	v_pk_add_f32 v[70:71], v[70:71], v[118:119]
	s_and_b64 vcc, exec, s[6:7]
	global_store_dwordx4 v[128:129], v[70:73], off offset:512 sc1
	s_cbranch_vccnz .LBB0_166
.LBB0_166:
	v_pk_add_f32 v[68:69], v[68:69], v[116:117]
	v_pk_add_f32 v[66:67], v[66:67], v[114:115]
	s_and_b64 vcc, exec, s[6:7]
	s_mov_b64 s[36:37], 0
	global_store_dwordx4 v[128:129], v[66:69], off offset:576 sc1
	s_cbranch_vccnz .LBB0_168
	s_mov_b64 s[36:37], s[14:15]
.LBB0_168:
	s_cmp_eq_u64 s[36:37], 0
	s_cbranch_scc1 .LBB0_172
	v_mul_f32_e32 v132, v78, v78
	v_fmac_f32_e32 v132, v79, v79
	v_fmac_f32_e32 v132, v80, v80
	v_fmac_f32_e32 v132, v81, v81
	v_fmac_f32_e32 v132, v74, v74
	v_fmac_f32_e32 v132, v75, v75
	v_fmac_f32_e32 v132, v76, v76
	v_fmac_f32_e32 v132, v77, v77
	v_fmac_f32_e32 v132, v70, v70
	v_fmac_f32_e32 v132, v71, v71
	v_fmac_f32_e32 v132, v72, v72
	v_fmac_f32_e32 v132, v73, v73
	v_fmac_f32_e32 v132, v66, v66
	v_fmac_f32_e32 v132, v67, v67
	v_fmac_f32_e32 v132, v68, v68
	v_fmac_f32_e32 v132, v69, v69
	v_cvt_pk_bf16_f32 v78, v78, v79
	v_cvt_pk_bf16_f32 v79, v80, v81
	v_cvt_pk_bf16_f32 v80, v74, v75
	v_cvt_pk_bf16_f32 v81, v76, v77
	v_cvt_pk_bf16_f32 v70, v70, v71
	v_cvt_pk_bf16_f32 v71, v72, v73
	v_cvt_pk_bf16_f32 v72, v66, v67
	v_cvt_pk_bf16_f32 v73, v68, v69
	v_add_co_u32_e32 v126, vcc, v220, v126
	s_nop 1
	v_addc_co_u32_e32 v127, vcc, 0, v127, vcc
	v_permlane16_swap_b32_e32 v78, v80
	v_permlane16_swap_b32_e32 v79, v81
	v_permlane16_swap_b32_e32 v70, v72
	v_permlane16_swap_b32_e32 v71, v73
	global_store_dwordx4 v[126:127], v[78:81], off sc1
	global_store_dwordx4 v[126:127], v[70:73], off offset:256 sc1
	v_and_b32_e32 v67, 64, v204
	v_xor_b32_e32 v66, 16, v204
	v_add_u32_e32 v67, 64, v67
	v_cmp_lt_i32_e32 vcc, v66, v67
	v_xor_b32_e32 v68, 32, v204
	s_nop 0
	v_cndmask_b32_e32 v66, v204, v66, vcc
	v_lshlrev_b32_e32 v66, 2, v66
	ds_bpermute_b32 v66, v66, v132
	v_cmp_lt_i32_e32 vcc, v68, v67
	s_waitcnt lgkmcnt(0)
	v_add_f32_e32 v66, v132, v66
	v_cndmask_b32_e32 v67, v204, v68, vcc
	v_lshlrev_b32_e32 v67, 2, v67
	ds_bpermute_b32 v67, v67, v66
	s_and_saveexec_b64 s[38:39], s[8:9]
	s_cbranch_execz .LBB0_171
	v_lshl_add_u64 v[68:69], v[190:191], 2, s[36:37]
	s_waitcnt lgkmcnt(0)
	v_add_f32_e32 v66, v66, v67
	global_atomic_add_f32 v[68:69], v66, off offset:192

; __device__ __forceinline__ unsigned cvt_pk_bf16(float lo, float hi) { unsigned r; asm volatile("v_cvt_pk_bf16_f32 %0, %1, %2" : "=v"(r) : "v"(lo), "v"(hi)); return r; }
; #define EO_LOAD(rr, slot) do { const size_t o_ = (size_t)(row0 + ((rr) >> 2) * 128 + ((rr) & 3) * 16) * DM + col0; _Pragma("unroll") for (int q_ = 0; q_ < 4; ++q_) xr[slot][q_] = *(const f32x4*)(Xin + o_ + (q_ >> 1) * 128 + (q_ & 1) * 16); } while (0)
;     __device__ __forceinline__ void operator()(const f32x4 (&acc)[2][2][4][2], const pg8::Unit& u, int wr, int wc, int fr, int fq) const {
;     ...
;         for (int rr = 0; rr < 8; ++rr) { const int ai = rr >> 2, m = rr & 3, row = row0 + ai * 128 + m * 16; const size_t o = (size_t)row * DM + col0; float s = 0.f;
;             if (rr + 2 < 8) EO_LOAD(rr + 2, (rr + 2) % 3);
; #pragma unroll
;             for (int q = 0; q < 4; ++q) { const int bj = q >> 1, n = q & 1; const size_t idx = o + bj * 128 + n * 16; const f32x4 v = xr[rr % 3][q] + acc[ai][bj][m][n]; *(f32x4*)(Out + idx) = v;
;                 if (ssq) { u32x2 w; w.x = cvt_pk_bf16(v[0], v[1]); w.y = cvt_pk_bf16(v[2], v[3]); *(u32x2*)(HBo + idx) = w; s += (v[0] * v[0] + v[1] * v[1]) + (v[2] * v[2] + v[3] * v[3]); } }
;             if (ssq) { s += __shfl_xor(s, 16); s += __shfl_xor(s, 32); if (fq == 0) atomicAdd(ssq + row, s); } }
.Lmy_eo_r4_d:
	v_pk_add_f32 v[64:65], v[64:65], v[112:113]
	v_pk_add_f32 v[62:63], v[62:63], v[110:111]
	v_lshl_add_u64 v[112:113], v[118:119], 2, s[86:87]
	v_mov_b32_e32 v116, 0
	s_and_b64 vcc, exec, s[6:7]
	v_lshl_add_u64 v[110:111], v[118:119], 1, s[22:23]
	v_readlane_b32 s73, v251, 7
	v_readlane_b32 s74, v251, 8
	v_readlane_b32 s75, v251, 9
	v_readlane_b32 s76, v251, 10
	v_readlane_b32 s77, v251, 11
	v_readlane_b32 s78, v251, 12
	v_readlane_b32 s79, v251, 13
	v_readlane_b32 s80, v251, 14
	v_readlane_b32 s81, v251, 15
	v_readlane_b32 s82, v251, 16
	v_readlane_b32 s83, v251, 17
	v_readlane_b32 s84, v251, 18
	v_readlane_b32 s85, v251, 19
	global_store_dwordx4 v[112:113], v[62:65], off sc1
	s_cbranch_vccnz .LBB0_174
.LBB0_174:
	v_pk_add_f32 v[60:61], v[60:61], v[108:109]
	v_pk_add_f32 v[58:59], v[58:59], v[106:107]
	s_and_b64 vcc, exec, s[6:7]
	global_store_dwordx4 v[112:113], v[58:61], off offset:64 sc1
	s_cbranch_vccnz .LBB0_176
.LBB0_176:
	v_pk_add_f32 v[56:57], v[56:57], v[104:105]
	v_pk_add_f32 v[54:55], v[54:55], v[102:103]
	s_and_b64 vcc, exec, s[6:7]
	global_store_dwordx4 v[112:113], v[54:57], off offset:512 sc1
	s_cbranch_vccnz .LBB0_178
.LBB0_178:
	v_pk_add_f32 v[52:53], v[52:53], v[100:101]
	v_pk_add_f32 v[50:51], v[50:51], v[98:99]
	s_and_b64 vcc, exec, s[6:7]
	s_mov_b64 s[36:37], 0
	global_store_dwordx4 v[112:113], v[50:53], off offset:576 sc1
	s_cbranch_vccnz .LBB0_180
	s_mov_b64 s[36:37], s[14:15]
.LBB0_180:
	s_cmp_eq_u64 s[36:37], 0
	s_cbranch_scc1 .LBB0_184
	v_mul_f32_e32 v116, v62, v62
	v_fmac_f32_e32 v116, v63, v63
	v_fmac_f32_e32 v116, v64, v64
	v_fmac_f32_e32 v116, v65, v65
	v_fmac_f32_e32 v116, v58, v58
	v_fmac_f32_e32 v116, v59, v59
	v_fmac_f32_e32 v116, v60, v60
	v_fmac_f32_e32 v116, v61, v61
	v_fmac_f32_e32 v116, v54, v54
	v_fmac_f32_e32 v116, v55, v55
	v_fmac_f32_e32 v116, v56, v56
	v_fmac_f32_e32 v116, v57, v57
	v_fmac_f32_e32 v116, v50, v50
	v_fmac_f32_e32 v116, v51, v51
	v_fmac_f32_e32 v116, v52, v52
	v_fmac_f32_e32 v116, v53, v53
	v_cvt_pk_bf16_f32 v62, v62, v63
	v_cvt_pk_bf16_f32 v63, v64, v65
	v_cvt_pk_bf16_f32 v64, v58, v59
	v_cvt_pk_bf16_f32 v65, v60, v61
	v_cvt_pk_bf16_f32 v54, v54, v55
	v_cvt_pk_bf16_f32 v55, v56, v57
	v_cvt_pk_bf16_f32 v56, v50, v51
	v_cvt_pk_bf16_f32 v57, v52, v53
	v_add_co_u32_e32 v110, vcc, v220, v110
	s_nop 1
	v_addc_co_u32_e32 v111, vcc, 0, v111, vcc
	v_permlane16_swap_b32_e32 v62, v64
	v_permlane16_swap_b32_e32 v63, v65
	v_permlane16_swap_b32_e32 v54, v56
	v_permlane16_swap_b32_e32 v55, v57
	global_store_dwordx4 v[110:111], v[62:65], off sc1
	global_store_dwordx4 v[110:111], v[54:57], off offset:256 sc1
	v_and_b32_e32 v51, 64, v204
	v_xor_b32_e32 v50, 16, v204
	v_add_u32_e32 v51, 64, v51
	v_cmp_lt_i32_e32 vcc, v50, v51
	v_xor_b32_e32 v52, 32, v204
	s_nop 0
	v_cndmask_b32_e32 v50, v204, v50, vcc
	v_lshlrev_b32_e32 v50, 2, v50
	ds_bpermute_b32 v50, v50, v116
	v_cmp_lt_i32_e32 vcc, v52, v51
	s_waitcnt lgkmcnt(0)
	v_add_f32_e32 v50, v116, v50
	v_cndmask_b32_e32 v51, v204, v52, vcc
	v_lshlrev_b32_e32 v51, 2, v51
	ds_bpermute_b32 v51, v51, v50
	s_and_saveexec_b64 s[38:39], s[8:9]
	s_cbranch_execz .LBB0_183
	v_lshl_add_u64 v[52:53], v[190:191], 2, s[36:37]
	s_waitcnt lgkmcnt(0)
	v_add_f32_e32 v50, v50, v51
	global_atomic_add_f32 v[52:53], v50, off offset:512

; __device__ __forceinline__ unsigned cvt_pk_bf16(float lo, float hi) { unsigned r; asm volatile("v_cvt_pk_bf16_f32 %0, %1, %2" : "=v"(r) : "v"(lo), "v"(hi)); return r; }
; #define EO_LOAD(rr, slot) do { const size_t o_ = (size_t)(row0 + ((rr) >> 2) * 128 + ((rr) & 3) * 16) * DM + col0; _Pragma("unroll") for (int q_ = 0; q_ < 4; ++q_) xr[slot][q_] = *(const f32x4*)(Xin + o_ + (q_ >> 1) * 128 + (q_ & 1) * 16); } while (0)
;     __device__ __forceinline__ void operator()(const f32x4 (&acc)[2][2][4][2], const pg8::Unit& u, int wr, int wc, int fr, int fq) const {
;     ...
;         for (int rr = 0; rr < 8; ++rr) { const int ai = rr >> 2, m = rr & 3, row = row0 + ai * 128 + m * 16; const size_t o = (size_t)row * DM + col0; float s = 0.f;
;             if (rr + 2 < 8) EO_LOAD(rr + 2, (rr + 2) % 3);
; #pragma unroll
;             for (int q = 0; q < 4; ++q) { const int bj = q >> 1, n = q & 1; const size_t idx = o + bj * 128 + n * 16; const f32x4 v = xr[rr % 3][q] + acc[ai][bj][m][n]; *(f32x4*)(Out + idx) = v;
;                 if (ssq) { u32x2 w; w.x = cvt_pk_bf16(v[0], v[1]); w.y = cvt_pk_bf16(v[2], v[3]); *(u32x2*)(HBo + idx) = w; s += (v[0] * v[0] + v[1] * v[1]) + (v[2] * v[2] + v[3] * v[3]); } }
;             if (ssq) { s += __shfl_xor(s, 16); s += __shfl_xor(s, 32); if (fq == 0) atomicAdd(ssq + row, s); } }
.Lmy_eo_r5_d:
	v_pk_add_f32 v[48:49], v[48:49], v[96:97]
	v_pk_add_f32 v[46:47], v[46:47], v[94:95]
	v_lshl_add_u64 v[96:97], v[102:103], 2, s[86:87]
	v_mov_b32_e32 v100, 0
	s_and_b64 vcc, exec, s[6:7]
	v_lshl_add_u64 v[94:95], v[102:103], 1, s[22:23]
	v_readlane_b32 s73, v251, 7
	v_readlane_b32 s74, v251, 8
	v_readlane_b32 s75, v251, 9
	v_readlane_b32 s76, v251, 10
	v_readlane_b32 s77, v251, 11
	v_readlane_b32 s78, v251, 12
	v_readlane_b32 s79, v251, 13
	v_readlane_b32 s80, v251, 14
	v_readlane_b32 s81, v251, 15
	v_readlane_b32 s82, v251, 16
	v_readlane_b32 s83, v251, 17
	v_readlane_b32 s84, v251, 18
	v_readlane_b32 s85, v251, 19
	global_store_dwordx4 v[96:97], v[46:49], off sc1
	s_cbranch_vccnz .LBB0_186
.LBB0_186:
	v_pk_add_f32 v[44:45], v[44:45], v[92:93]
	v_pk_add_f32 v[42:43], v[42:43], v[90:91]
	s_and_b64 vcc, exec, s[6:7]
	global_store_dwordx4 v[96:97], v[42:45], off offset:64 sc1
	s_cbranch_vccnz .LBB0_188
.LBB0_188:
	v_pk_add_f32 v[40:41], v[40:41], v[88:89]
	v_pk_add_f32 v[38:39], v[38:39], v[86:87]
	s_and_b64 vcc, exec, s[6:7]
	global_store_dwordx4 v[96:97], v[38:41], off offset:512 sc1
	s_cbranch_vccnz .LBB0_190
.LBB0_190:
	v_pk_add_f32 v[36:37], v[36:37], v[84:85]
	v_pk_add_f32 v[34:35], v[34:35], v[82:83]
	s_and_b64 vcc, exec, s[6:7]
	s_mov_b64 s[36:37], 0
	global_store_dwordx4 v[96:97], v[34:37], off offset:576 sc1
	s_cbranch_vccnz .LBB0_192
	s_mov_b64 s[36:37], s[14:15]
.LBB0_192:
	s_cmp_eq_u64 s[36:37], 0
	s_cbranch_scc1 .LBB0_196
	v_mul_f32_e32 v100, v46, v46
	v_fmac_f32_e32 v100, v47, v47
	v_fmac_f32_e32 v100, v48, v48
	v_fmac_f32_e32 v100, v49, v49
	v_fmac_f32_e32 v100, v42, v42
	v_fmac_f32_e32 v100, v43, v43
	v_fmac_f32_e32 v100, v44, v44
	v_fmac_f32_e32 v100, v45, v45
	v_fmac_f32_e32 v100, v38, v38
	v_fmac_f32_e32 v100, v39, v39
	v_fmac_f32_e32 v100, v40, v40
	v_fmac_f32_e32 v100, v41, v41
	v_fmac_f32_e32 v100, v34, v34
	v_fmac_f32_e32 v100, v35, v35
	v_fmac_f32_e32 v100, v36, v36
	v_fmac_f32_e32 v100, v37, v37
	v_cvt_pk_bf16_f32 v46, v46, v47
	v_cvt_pk_bf16_f32 v47, v48, v49
	v_cvt_pk_bf16_f32 v48, v42, v43
	v_cvt_pk_bf16_f32 v49, v44, v45
	v_cvt_pk_bf16_f32 v38, v38, v39
	v_cvt_pk_bf16_f32 v39, v40, v41
	v_cvt_pk_bf16_f32 v40, v34, v35
	v_cvt_pk_bf16_f32 v41, v36, v37
	v_add_co_u32_e32 v94, vcc, v220, v94
	s_nop 1
	v_addc_co_u32_e32 v95, vcc, 0, v95, vcc
	v_permlane16_swap_b32_e32 v46, v48
	v_permlane16_swap_b32_e32 v47, v49
	v_permlane16_swap_b32_e32 v38, v40
	v_permlane16_swap_b32_e32 v39, v41
	global_store_dwordx4 v[94:95], v[46:49], off sc1
	global_store_dwordx4 v[94:95], v[38:41], off offset:256 sc1
	v_and_b32_e32 v35, 64, v204
	v_xor_b32_e32 v34, 16, v204
	v_add_u32_e32 v35, 64, v35
	v_cmp_lt_i32_e32 vcc, v34, v35
	v_xor_b32_e32 v36, 32, v204
	s_nop 0
	v_cndmask_b32_e32 v34, v204, v34, vcc
	v_lshlrev_b32_e32 v34, 2, v34
	ds_bpermute_b32 v34, v34, v100
	v_cmp_lt_i32_e32 vcc, v36, v35
	s_waitcnt lgkmcnt(0)
	v_add_f32_e32 v34, v100, v34
	v_cndmask_b32_e32 v35, v204, v36, vcc
	v_lshlrev_b32_e32 v35, 2, v35
	ds_bpermute_b32 v35, v35, v34
	s_and_saveexec_b64 s[38:39], s[8:9]
	s_cbranch_execz .LBB0_195
	v_lshl_add_u64 v[36:37], v[190:191], 2, s[36:37]
	s_waitcnt lgkmcnt(0)
	v_add_f32_e32 v34, v34, v35
	global_atomic_add_f32 v[36:37], v34, off offset:576

; __device__ __forceinline__ unsigned cvt_pk_bf16(float lo, float hi) { unsigned r; asm volatile("v_cvt_pk_bf16_f32 %0, %1, %2" : "=v"(r) : "v"(lo), "v"(hi)); return r; }
; #define EO_LOAD(rr, slot) do { const size_t o_ = (size_t)(row0 + ((rr) >> 2) * 128 + ((rr) & 3) * 16) * DM + col0; _Pragma("unroll") for (int q_ = 0; q_ < 4; ++q_) xr[slot][q_] = *(const f32x4*)(Xin + o_ + (q_ >> 1) * 128 + (q_ & 1) * 16); } while (0)
;     __device__ __forceinline__ void operator()(const f32x4 (&acc)[2][2][4][2], const pg8::Unit& u, int wr, int wc, int fr, int fq) const {
;     ...
;         for (int rr = 0; rr < 8; ++rr) { const int ai = rr >> 2, m = rr & 3, row = row0 + ai * 128 + m * 16; const size_t o = (size_t)row * DM + col0; float s = 0.f;
;             if (rr + 2 < 8) EO_LOAD(rr + 2, (rr + 2) % 3);
; #pragma unroll
;             for (int q = 0; q < 4; ++q) { const int bj = q >> 1, n = q & 1; const size_t idx = o + bj * 128 + n * 16; const f32x4 v = xr[rr % 3][q] + acc[ai][bj][m][n]; *(f32x4*)(Out + idx) = v;
;                 if (ssq) { u32x2 w; w.x = cvt_pk_bf16(v[0], v[1]); w.y = cvt_pk_bf16(v[2], v[3]); *(u32x2*)(HBo + idx) = w; s += (v[0] * v[0] + v[1] * v[1]) + (v[2] * v[2] + v[3] * v[3]); } }
;             if (ssq) { s += __shfl_xor(s, 16); s += __shfl_xor(s, 32); if (fq == 0) atomicAdd(ssq + row, s); } }
.Lmy_eo_r6_d:
	v_pk_add_f32 v[32:33], v[32:33], v[80:81]
	v_pk_add_f32 v[30:31], v[30:31], v[78:79]
	v_lshl_add_u64 v[36:37], v[34:35], 2, s[86:87]
	v_mov_b32_e32 v38, 0
	s_and_b64 vcc, exec, s[6:7]
	v_lshl_add_u64 v[34:35], v[34:35], 1, s[22:23]
	v_readlane_b32 s73, v251, 7
	v_readlane_b32 s74, v251, 8
	v_readlane_b32 s75, v251, 9
	v_readlane_b32 s76, v251, 10
	v_readlane_b32 s77, v251, 11
	v_readlane_b32 s78, v251, 12
	v_readlane_b32 s79, v251, 13
	v_readlane_b32 s80, v251, 14
	v_readlane_b32 s81, v251, 15
	v_readlane_b32 s82, v251, 16
	v_readlane_b32 s83, v251, 17
	v_readlane_b32 s84, v251, 18
	v_readlane_b32 s85, v251, 19
	global_store_dwordx4 v[36:37], v[30:33], off sc1
	s_cbranch_vccnz .LBB0_198
.LBB0_198:
	v_pk_add_f32 v[28:29], v[28:29], v[76:77]
	v_pk_add_f32 v[26:27], v[26:27], v[74:75]
	s_and_b64 vcc, exec, s[6:7]
	global_store_dwordx4 v[36:37], v[26:29], off offset:64 sc1
	s_cbranch_vccnz .LBB0_200
.LBB0_200:
	v_pk_add_f32 v[24:25], v[24:25], v[72:73]
	v_pk_add_f32 v[22:23], v[22:23], v[70:71]
	s_and_b64 vcc, exec, s[6:7]
	global_store_dwordx4 v[36:37], v[22:25], off offset:512 sc1
	s_cbranch_vccnz .LBB0_202
.LBB0_202:
	v_pk_add_f32 v[20:21], v[20:21], v[68:69]
	v_pk_add_f32 v[18:19], v[18:19], v[66:67]
	s_and_b64 vcc, exec, s[6:7]
	s_mov_b64 s[36:37], 0
	global_store_dwordx4 v[36:37], v[18:21], off offset:576 sc1
	s_cbranch_vccnz .LBB0_204
	s_mov_b64 s[36:37], s[14:15]
.LBB0_204:
	s_cmp_eq_u64 s[36:37], 0
	s_cbranch_scc1 .LBB0_208
	v_mul_f32_e32 v38, v30, v30
	v_fmac_f32_e32 v38, v31, v31
	v_fmac_f32_e32 v38, v32, v32
	v_fmac_f32_e32 v38, v33, v33
	v_fmac_f32_e32 v38, v26, v26
	v_fmac_f32_e32 v38, v27, v27
	v_fmac_f32_e32 v38, v28, v28
	v_fmac_f32_e32 v38, v29, v29
	v_fmac_f32_e32 v38, v22, v22
	v_fmac_f32_e32 v38, v23, v23
	v_fmac_f32_e32 v38, v24, v24
	v_fmac_f32_e32 v38, v25, v25
	v_fmac_f32_e32 v38, v18, v18
	v_fmac_f32_e32 v38, v19, v19
	v_fmac_f32_e32 v38, v20, v20
	v_fmac_f32_e32 v38, v21, v21
	v_cvt_pk_bf16_f32 v30, v30, v31
	v_cvt_pk_bf16_f32 v31, v32, v33
	v_cvt_pk_bf16_f32 v32, v26, v27
	v_cvt_pk_bf16_f32 v33, v28, v29
	v_cvt_pk_bf16_f32 v22, v22, v23
	v_cvt_pk_bf16_f32 v23, v24, v25
	v_cvt_pk_bf16_f32 v24, v18, v19
	v_cvt_pk_bf16_f32 v25, v20, v21
	v_add_co_u32_e32 v34, vcc, v220, v34
	s_nop 1
	v_addc_co_u32_e32 v35, vcc, 0, v35, vcc
	v_permlane16_swap_b32_e32 v30, v32
	v_permlane16_swap_b32_e32 v31, v33
	v_permlane16_swap_b32_e32 v22, v24
	v_permlane16_swap_b32_e32 v23, v25
	global_store_dwordx4 v[34:35], v[30:33], off sc1
	global_store_dwordx4 v[34:35], v[22:25], off offset:256 sc1
	v_and_b32_e32 v19, 64, v204
	v_xor_b32_e32 v18, 16, v204
	v_add_u32_e32 v19, 64, v19
	v_cmp_lt_i32_e32 vcc, v18, v19
	v_xor_b32_e32 v20, 32, v204
	s_nop 0
	v_cndmask_b32_e32 v18, v204, v18, vcc
	v_lshlrev_b32_e32 v18, 2, v18
	ds_bpermute_b32 v18, v18, v38
	v_cmp_lt_i32_e32 vcc, v20, v19
	s_waitcnt lgkmcnt(0)
	v_add_f32_e32 v18, v38, v18
	v_cndmask_b32_e32 v19, v204, v20, vcc
	v_lshlrev_b32_e32 v19, 2, v19
	ds_bpermute_b32 v19, v19, v18
	s_and_saveexec_b64 s[38:39], s[8:9]
	s_cbranch_execz .LBB0_207
	v_lshl_add_u64 v[20:21], v[190:191], 2, s[36:37]
	s_waitcnt lgkmcnt(0)
	v_add_f32_e32 v18, v18, v19
	global_atomic_add_f32 v[20:21], v18, off offset:640

; __device__ __forceinline__ unsigned cvt_pk_bf16(float lo, float hi) { unsigned r; asm volatile("v_cvt_pk_bf16_f32 %0, %1, %2" : "=v"(r) : "v"(lo), "v"(hi)); return r; }
; #define EO_LOAD(rr, slot) do { const size_t o_ = (size_t)(row0 + ((rr) >> 2) * 128 + ((rr) & 3) * 16) * DM + col0; _Pragma("unroll") for (int q_ = 0; q_ < 4; ++q_) xr[slot][q_] = *(const f32x4*)(Xin + o_ + (q_ >> 1) * 128 + (q_ & 1) * 16); } while (0)
;     __device__ __forceinline__ void operator()(const f32x4 (&acc)[2][2][4][2], const pg8::Unit& u, int wr, int wc, int fr, int fq) const {
;     ...
;         for (int rr = 0; rr < 8; ++rr) { const int ai = rr >> 2, m = rr & 3, row = row0 + ai * 128 + m * 16; const size_t o = (size_t)row * DM + col0; float s = 0.f;
;             if (rr + 2 < 8) EO_LOAD(rr + 2, (rr + 2) % 3);
; #pragma unroll
;             for (int q = 0; q < 4; ++q) { const int bj = q >> 1, n = q & 1; const size_t idx = o + bj * 128 + n * 16; const f32x4 v = xr[rr % 3][q] + acc[ai][bj][m][n]; *(f32x4*)(Out + idx) = v;
;                 if (ssq) { u32x2 w; w.x = cvt_pk_bf16(v[0], v[1]); w.y = cvt_pk_bf16(v[2], v[3]); *(u32x2*)(HBo + idx) = w; s += (v[0] * v[0] + v[1] * v[1]) + (v[2] * v[2] + v[3] * v[3]); } }
;             if (ssq) { s += __shfl_xor(s, 16); s += __shfl_xor(s, 32); if (fq == 0) atomicAdd(ssq + row, s); } }
.Lmy_eo_r7_d:
	v_pk_add_f32 v[16:17], v[16:17], v[64:65]
	v_pk_add_f32 v[14:15], v[14:15], v[62:63]
	v_lshl_add_u64 v[20:21], v[18:19], 2, s[86:87]
	v_mov_b32_e32 v22, 0
	s_and_b64 vcc, exec, s[6:7]
	v_lshl_add_u64 v[18:19], v[18:19], 1, s[22:23]
	v_readlane_b32 s73, v251, 7
	v_readlane_b32 s74, v251, 8
	v_readlane_b32 s75, v251, 9
	v_readlane_b32 s76, v251, 10
	v_readlane_b32 s77, v251, 11
	v_readlane_b32 s78, v251, 12
	v_readlane_b32 s79, v251, 13
	v_readlane_b32 s80, v251, 14
	v_readlane_b32 s81, v251, 15
	v_readlane_b32 s82, v251, 16
	v_readlane_b32 s83, v251, 17
	v_readlane_b32 s84, v251, 18
	v_readlane_b32 s85, v251, 19
	global_store_dwordx4 v[20:21], v[14:17], off sc1
	s_cbranch_vccnz .LBB0_210
.LBB0_210:
	v_readlane_b32 s20, v250, 9
	v_pk_add_f32 v[12:13], v[12:13], v[60:61]
	v_pk_add_f32 v[10:11], v[10:11], v[58:59]
	s_and_b64 vcc, exec, s[6:7]
	v_readlane_b32 s21, v250, 10
	global_store_dwordx4 v[20:21], v[10:13], off offset:64 sc1
	s_cbranch_vccnz .LBB0_212
.LBB0_212:
	v_pk_add_f32 v[8:9], v[8:9], v[56:57]
	v_pk_add_f32 v[6:7], v[6:7], v[54:55]
	s_and_b64 vcc, exec, s[6:7]
	global_store_dwordx4 v[20:21], v[6:9], off offset:512 sc1
	s_cbranch_vccnz .LBB0_214
.LBB0_214:
	v_pk_add_f32 v[4:5], v[4:5], v[52:53]
	v_pk_add_f32 v[2:3], v[2:3], v[50:51]
	s_and_b64 vcc, exec, s[6:7]
	s_mov_b64 s[6:7], 0
	global_store_dwordx4 v[20:21], v[2:5], off offset:576 sc1
	s_cbranch_vccnz .LBB0_216
	s_mov_b64 s[6:7], s[14:15]
.LBB0_216:
	s_cmp_eq_u64 s[6:7], 0
	s_cbranch_scc1 .LBB0_220
	v_mul_f32_e32 v22, v14, v14
	v_fmac_f32_e32 v22, v15, v15
	v_fmac_f32_e32 v22, v16, v16
	v_fmac_f32_e32 v22, v17, v17
	v_fmac_f32_e32 v22, v10, v10
	v_fmac_f32_e32 v22, v11, v11
	v_fmac_f32_e32 v22, v12, v12
	v_fmac_f32_e32 v22, v13, v13
	v_fmac_f32_e32 v22, v6, v6
	v_fmac_f32_e32 v22, v7, v7
	v_fmac_f32_e32 v22, v8, v8
	v_fmac_f32_e32 v22, v9, v9
	v_fmac_f32_e32 v22, v2, v2
	v_fmac_f32_e32 v22, v3, v3
	v_fmac_f32_e32 v22, v4, v4
	v_fmac_f32_e32 v22, v5, v5
	v_cvt_pk_bf16_f32 v14, v14, v15
	v_cvt_pk_bf16_f32 v15, v16, v17
	v_cvt_pk_bf16_f32 v16, v10, v11
	v_cvt_pk_bf16_f32 v17, v12, v13
	v_cvt_pk_bf16_f32 v6, v6, v7
	v_cvt_pk_bf16_f32 v7, v8, v9
	v_cvt_pk_bf16_f32 v8, v2, v3
	v_cvt_pk_bf16_f32 v9, v4, v5
	v_add_co_u32_e32 v18, vcc, v220, v18
	s_nop 1
	v_addc_co_u32_e32 v19, vcc, 0, v19, vcc
	v_permlane16_swap_b32_e32 v14, v16
	v_permlane16_swap_b32_e32 v15, v17
	v_permlane16_swap_b32_e32 v6, v8
	v_permlane16_swap_b32_e32 v7, v9
	global_store_dwordx4 v[18:19], v[14:17], off sc1
	global_store_dwordx4 v[18:19], v[6:9], off offset:256 sc1
	v_and_b32_e32 v3, 64, v204
	v_xor_b32_e32 v2, 16, v204
	v_add_u32_e32 v3, 64, v3
	v_cmp_lt_i32_e32 vcc, v2, v3
	v_xor_b32_e32 v4, 32, v204
	s_nop 0
	v_cndmask_b32_e32 v2, v204, v2, vcc
	v_lshlrev_b32_e32 v2, 2, v2
	ds_bpermute_b32 v2, v2, v22
	v_cmp_lt_i32_e32 vcc, v4, v3
	s_waitcnt lgkmcnt(0)
	v_add_f32_e32 v2, v22, v2
	v_cndmask_b32_e32 v3, v204, v4, vcc
	v_lshlrev_b32_e32 v3, 2, v3
	ds_bpermute_b32 v3, v3, v2
	s_and_saveexec_b64 s[36:37], s[8:9]
	s_cbranch_execz .LBB0_219
	v_lshl_add_u64 v[4:5], v[190:191], 2, s[6:7]
	s_waitcnt lgkmcnt(0)
	v_add_f32_e32 v2, v2, v3
	global_atomic_add_f32 v[4:5], v2, off offset:704
